# lever 7 (instruction selection): GEMM tile start clears the 128 accumulators with 64 v_mov_b64 instead of 128 v_mov_b32
# speedup vs baseline: 1.0024x; 1.0024x over previous
.LBB0_135:
	s_ashr_i32 s17, s16, 31
	s_lshl_b64 s[18:19], s[16:17], 20
	s_add_u32 s18, s28, s18
	s_addc_u32 s19, s29, s19
	s_and_b64 s[20:21], s[4:5], exec
	s_cselect_b32 s17, s19, s23
	s_cselect_b32 s44, s18, s22
	s_ashr_i32 s15, s14, 31
	s_lshl_b64 s[20:21], s[14:15], 20
	s_add_u32 s20, s30, s20
	s_addc_u32 s21, s31, s21
	s_and_b64 s[26:27], s[4:5], exec
	s_cselect_b32 s15, s21, s25
	s_cselect_b32 s45, s20, s24
	s_add_u32 s22, s22, 0x80080
	s_addc_u32 s23, s23, 0
	s_add_u32 s50, s24, 0x100
	s_addc_u32 s51, s25, 0
	s_mov_b32 s52, -2
	v_mov_b64_e32 v[0:1], 0
	v_mov_b64_e32 v[2:3], 0
	v_mov_b64_e32 v[4:5], 0
	v_mov_b64_e32 v[6:7], 0
	v_mov_b64_e32 v[8:9], 0
	v_mov_b64_e32 v[10:11], 0
	v_mov_b64_e32 v[12:13], 0
	v_mov_b64_e32 v[14:15], 0
	v_mov_b64_e32 v[16:17], 0
	v_mov_b64_e32 v[18:19], 0
	v_mov_b64_e32 v[20:21], 0
	v_mov_b64_e32 v[22:23], 0
	v_mov_b64_e32 v[24:25], 0
	v_mov_b64_e32 v[26:27], 0
	v_mov_b64_e32 v[28:29], 0
	v_mov_b64_e32 v[30:31], 0
	v_mov_b64_e32 v[32:33], 0
	v_mov_b64_e32 v[34:35], 0
	v_mov_b64_e32 v[36:37], 0
	v_mov_b64_e32 v[38:39], 0
	v_mov_b64_e32 v[40:41], 0
	v_mov_b64_e32 v[42:43], 0
	v_mov_b64_e32 v[44:45], 0
	v_mov_b64_e32 v[46:47], 0
	v_mov_b64_e32 v[48:49], 0
	v_mov_b64_e32 v[50:51], 0
	v_mov_b64_e32 v[52:53], 0
	v_mov_b64_e32 v[54:55], 0
	v_mov_b64_e32 v[56:57], 0
	v_mov_b64_e32 v[58:59], 0
	v_mov_b64_e32 v[60:61], 0
	v_mov_b64_e32 v[62:63], 0
	v_mov_b64_e32 v[64:65], 0
	v_mov_b64_e32 v[66:67], 0
	v_mov_b64_e32 v[68:69], 0
	v_mov_b64_e32 v[70:71], 0
	v_mov_b64_e32 v[72:73], 0
	v_mov_b64_e32 v[74:75], 0
	v_mov_b64_e32 v[76:77], 0
	v_mov_b64_e32 v[78:79], 0
	v_mov_b64_e32 v[80:81], 0
	v_mov_b64_e32 v[82:83], 0
	v_mov_b64_e32 v[84:85], 0
	v_mov_b64_e32 v[86:87], 0
	v_mov_b64_e32 v[88:89], 0
	v_mov_b64_e32 v[90:91], 0
	v_mov_b64_e32 v[92:93], 0
	v_mov_b64_e32 v[94:95], 0
	v_mov_b64_e32 v[96:97], 0
	v_mov_b64_e32 v[98:99], 0
	v_mov_b64_e32 v[100:101], 0
	v_mov_b64_e32 v[102:103], 0
	v_mov_b64_e32 v[104:105], 0
	v_mov_b64_e32 v[106:107], 0
	v_mov_b64_e32 v[108:109], 0
	v_mov_b64_e32 v[110:111], 0
	v_mov_b64_e32 v[112:113], 0
	v_mov_b64_e32 v[114:115], 0
	v_mov_b64_e32 v[116:117], 0
	v_mov_b64_e32 v[118:119], 0
	v_mov_b64_e32 v[120:121], 0
	v_mov_b64_e32 v[122:123], 0
	v_mov_b64_e32 v[124:125], 0
	v_mov_b64_e32 v[126:127], 0
	.p2align 6

.LBB0_212:
	s_add_u32 s52, s26, 0x100
	s_addc_u32 s53, s27, 0
	s_mov_b32 s56, -2
	v_mov_b64_e32 v[0:1], 0
	v_mov_b64_e32 v[2:3], 0
	v_mov_b64_e32 v[4:5], 0
	v_mov_b64_e32 v[6:7], 0
	v_mov_b64_e32 v[8:9], 0
	v_mov_b64_e32 v[10:11], 0
	v_mov_b64_e32 v[12:13], 0
	v_mov_b64_e32 v[14:15], 0
	v_mov_b64_e32 v[16:17], 0
	v_mov_b64_e32 v[18:19], 0
	v_mov_b64_e32 v[20:21], 0
	v_mov_b64_e32 v[22:23], 0
	v_mov_b64_e32 v[24:25], 0
	v_mov_b64_e32 v[26:27], 0
	v_mov_b64_e32 v[28:29], 0
	v_mov_b64_e32 v[30:31], 0
	v_mov_b64_e32 v[32:33], 0
	v_mov_b64_e32 v[34:35], 0
	v_mov_b64_e32 v[36:37], 0
	v_mov_b64_e32 v[38:39], 0
	v_mov_b64_e32 v[40:41], 0
	v_mov_b64_e32 v[42:43], 0
	v_mov_b64_e32 v[44:45], 0
	v_mov_b64_e32 v[46:47], 0
	v_mov_b64_e32 v[48:49], 0
	v_mov_b64_e32 v[50:51], 0
	v_mov_b64_e32 v[52:53], 0
	v_mov_b64_e32 v[54:55], 0
	v_mov_b64_e32 v[56:57], 0
	v_mov_b64_e32 v[58:59], 0
	v_mov_b64_e32 v[60:61], 0
	v_mov_b64_e32 v[62:63], 0
	v_mov_b64_e32 v[64:65], 0
	v_mov_b64_e32 v[66:67], 0
	v_mov_b64_e32 v[68:69], 0
	v_mov_b64_e32 v[70:71], 0
	v_mov_b64_e32 v[72:73], 0
	v_mov_b64_e32 v[74:75], 0
	v_mov_b64_e32 v[76:77], 0
	v_mov_b64_e32 v[78:79], 0
	v_mov_b64_e32 v[80:81], 0
	v_mov_b64_e32 v[82:83], 0
	v_mov_b64_e32 v[84:85], 0
	v_mov_b64_e32 v[86:87], 0
	v_mov_b64_e32 v[88:89], 0
	v_mov_b64_e32 v[90:91], 0
	v_mov_b64_e32 v[92:93], 0
	v_mov_b64_e32 v[94:95], 0
	v_mov_b64_e32 v[96:97], 0
	v_mov_b64_e32 v[98:99], 0
	v_mov_b64_e32 v[100:101], 0
	v_mov_b64_e32 v[102:103], 0
	v_mov_b64_e32 v[104:105], 0
	v_mov_b64_e32 v[106:107], 0
	v_mov_b64_e32 v[108:109], 0
	v_mov_b64_e32 v[110:111], 0
	v_mov_b64_e32 v[112:113], 0
	v_mov_b64_e32 v[114:115], 0
	v_mov_b64_e32 v[116:117], 0
	v_mov_b64_e32 v[118:119], 0
	v_mov_b64_e32 v[120:121], 0
	v_mov_b64_e32 v[122:123], 0
	v_mov_b64_e32 v[124:125], 0
	v_mov_b64_e32 v[126:127], 0
	.p2align 6

.LBB0_354:
	s_ashr_i32 s17, s16, 31
	s_lshl_b64 s[18:19], s[16:17], 20
	s_add_u32 s18, s4, s18
	s_addc_u32 s19, s5, s19
	s_and_b64 s[20:21], s[6:7], exec
	s_cselect_b32 s17, s19, s23
	s_cselect_b32 s42, s18, s22
	s_ashr_i32 s15, s14, 31
	s_lshl_b64 s[20:21], s[14:15], 20
	s_add_u32 s20, s28, s20
	s_addc_u32 s21, s29, s21
	s_and_b64 s[26:27], s[6:7], exec
	s_cselect_b32 s15, s21, s25
	s_cselect_b32 s43, s20, s24
	s_add_u32 s22, s22, 0x80080
	s_addc_u32 s23, s23, 0
	s_add_u32 s44, s24, 0x100
	s_addc_u32 s45, s25, 0
	s_mov_b32 s50, -2
	v_mov_b64_e32 v[0:1], 0
	v_mov_b64_e32 v[2:3], 0
	v_mov_b64_e32 v[4:5], 0
	v_mov_b64_e32 v[6:7], 0
	v_mov_b64_e32 v[8:9], 0
	v_mov_b64_e32 v[10:11], 0
	v_mov_b64_e32 v[12:13], 0
	v_mov_b64_e32 v[14:15], 0
	v_mov_b64_e32 v[16:17], 0
	v_mov_b64_e32 v[18:19], 0
	v_mov_b64_e32 v[20:21], 0
	v_mov_b64_e32 v[22:23], 0
	v_mov_b64_e32 v[24:25], 0
	v_mov_b64_e32 v[26:27], 0
	v_mov_b64_e32 v[28:29], 0
	v_mov_b64_e32 v[30:31], 0
	v_mov_b64_e32 v[32:33], 0
	v_mov_b64_e32 v[34:35], 0
	v_mov_b64_e32 v[36:37], 0
	v_mov_b64_e32 v[38:39], 0
	v_mov_b64_e32 v[40:41], 0
	v_mov_b64_e32 v[42:43], 0
	v_mov_b64_e32 v[44:45], 0
	v_mov_b64_e32 v[46:47], 0
	v_mov_b64_e32 v[48:49], 0
	v_mov_b64_e32 v[50:51], 0
	v_mov_b64_e32 v[52:53], 0
	v_mov_b64_e32 v[54:55], 0
	v_mov_b64_e32 v[56:57], 0
	v_mov_b64_e32 v[58:59], 0
	v_mov_b64_e32 v[60:61], 0
	v_mov_b64_e32 v[62:63], 0
	v_mov_b64_e32 v[64:65], 0
	v_mov_b64_e32 v[66:67], 0
	v_mov_b64_e32 v[68:69], 0
	v_mov_b64_e32 v[70:71], 0
	v_mov_b64_e32 v[72:73], 0
	v_mov_b64_e32 v[74:75], 0
	v_mov_b64_e32 v[76:77], 0
	v_mov_b64_e32 v[78:79], 0
	v_mov_b64_e32 v[80:81], 0
	v_mov_b64_e32 v[82:83], 0
	v_mov_b64_e32 v[84:85], 0
	v_mov_b64_e32 v[86:87], 0
	v_mov_b64_e32 v[88:89], 0
	v_mov_b64_e32 v[90:91], 0
	v_mov_b64_e32 v[92:93], 0
	v_mov_b64_e32 v[94:95], 0
	v_mov_b64_e32 v[96:97], 0
	v_mov_b64_e32 v[98:99], 0
	v_mov_b64_e32 v[100:101], 0
	v_mov_b64_e32 v[102:103], 0
	v_mov_b64_e32 v[104:105], 0
	v_mov_b64_e32 v[106:107], 0
	v_mov_b64_e32 v[108:109], 0
	v_mov_b64_e32 v[110:111], 0
	v_mov_b64_e32 v[112:113], 0
	v_mov_b64_e32 v[114:115], 0
	v_mov_b64_e32 v[116:117], 0
	v_mov_b64_e32 v[118:119], 0
	v_mov_b64_e32 v[120:121], 0
	v_mov_b64_e32 v[122:123], 0
	v_mov_b64_e32 v[124:125], 0
	v_mov_b64_e32 v[126:127], 0
	.p2align 6

.LBB0_449:
	v_lshrrev_b32_e32 v16, 1, v8
	v_and_b32_e32 v139, 24, v16
	v_and_b32_e32 v15, 15, v8
	v_lshlrev_b32_e32 v16, 1, v139
	v_lshlrev_b32_e32 v8, 2, v8
	v_lshl_or_b32 v138, s34, 6, v15
	v_lshl_or_b32 v15, v15, 6, v16
	s_lshl_b32 s36, s36, 5
	v_and_b32_e32 v8, 32, v8
	s_lshl_b32 s34, s34, 13
	v_bitop3_b32 v16, v15, s34, v8 bitop3:0xde
	s_and_b32 s34, s36, 0x60
	s_lshl_b32 s36, s34, 7
	s_add_i32 m0, s18, 0x18000
	v_lshl_add_u64 v[6:7], v[6:7], 0, s[84:85]
	v_bitop3_b32 v140, v15, s36, v8 bitop3:0xde
	s_waitcnt vmcnt(2)
	s_barrier
	global_load_lds_dwordx4 v[6:7], off
	v_lshl_add_u64 v[4:5], v[4:5], 0, s[84:85]
	s_add_i32 m0, s18, 0x1a000
	s_add_i32 s36, s18, 0x8000
	s_add_i32 s37, s18, 0xa000
	global_load_lds_dwordx4 v[4:5], off
	v_lshl_add_u64 v[2:3], v[2:3], 0, s[84:85]
	s_mov_b32 m0, s36
	s_add_u32 s38, s20, 0x20080
	global_load_lds_dwordx4 v[2:3], off
	v_lshl_add_u64 v[0:1], v[0:1], 0, s[84:85]
	s_mov_b32 m0, s37
	s_addc_u32 s39, s21, 0
	global_load_lds_dwordx4 v[0:1], off
	s_add_i32 m0, s18, 0x1c000
	v_lshl_add_u64 v[0:1], s[38:39], 0, v[192:193]
	global_load_lds_dwordx4 v[0:1], off
	v_lshl_add_u64 v[0:1], s[38:39], 0, v[132:133]
	s_add_i32 m0, s18, 0x1e000
	s_add_u32 s38, s24, s26
	global_load_lds_dwordx4 v[0:1], off
	v_lshlrev_b32_e32 v0, 13, v9
	v_and_b32_e32 v0, 0xffffc000, v0
	s_addc_u32 s39, s25, s27
	v_lshl_add_u32 v0, v10, 10, v0
	v_and_b32_e32 v1, 1, v9
	v_lshl_or_b32 v0, v1, 6, v0
	s_add_u32 s24, s38, 0x22a20080
	v_lshl_add_u32 v0, v11, 1, v0
	v_mov_b32_e32 v1, v193
	s_addc_u32 s25, s39, 0
	v_lshl_add_u64 v[134:135], s[24:25], 0, v[0:1]
	v_lshlrev_b32_e32 v0, 13, v12
	v_and_b32_e32 v0, 0xffffc000, v0
	s_add_u32 s22, s22, s78
	v_lshl_add_u32 v0, v13, 10, v0
	v_and_b32_e32 v1, 1, v12
	s_addc_u32 s23, s23, 0
	v_lshl_or_b32 v0, v1, 6, v0
	s_add_u32 s22, s22, s40
	s_waitcnt vmcnt(6)
	v_lshl_add_u32 v0, v14, 1, v0
	v_mov_b32_e32 v1, v193
	s_addc_u32 s23, s23, 0
	v_lshl_add_u64 v[136:137], s[24:25], 0, v[0:1]
	s_add_u32 s40, s22, 0x5f00100
	s_addc_u32 s41, s23, 0
	s_mov_b32 s42, -2
	s_mov_b64 s[22:23], 0
	v_add_u32_e32 v141, 0, v16
	s_waitcnt vmcnt(0)
	v_mov_b64_e32 v[0:1], 0
	v_mov_b64_e32 v[2:3], 0
	v_mov_b64_e32 v[4:5], 0
	v_mov_b64_e32 v[6:7], 0
	v_mov_b64_e32 v[8:9], 0
	v_mov_b64_e32 v[10:11], 0
	v_mov_b64_e32 v[12:13], 0
	v_mov_b64_e32 v[14:15], 0
	v_mov_b64_e32 v[16:17], 0
	v_mov_b64_e32 v[18:19], 0
	v_mov_b64_e32 v[20:21], 0
	v_mov_b64_e32 v[22:23], 0
	v_mov_b64_e32 v[24:25], 0
	v_mov_b64_e32 v[26:27], 0
	v_mov_b64_e32 v[28:29], 0
	v_mov_b64_e32 v[30:31], 0
	v_mov_b64_e32 v[32:33], 0
	v_mov_b64_e32 v[34:35], 0
	v_mov_b64_e32 v[36:37], 0
	v_mov_b64_e32 v[38:39], 0
	v_mov_b64_e32 v[40:41], 0
	v_mov_b64_e32 v[42:43], 0
	v_mov_b64_e32 v[44:45], 0
	v_mov_b64_e32 v[46:47], 0
	v_mov_b64_e32 v[48:49], 0
	v_mov_b64_e32 v[50:51], 0
	v_mov_b64_e32 v[52:53], 0
	v_mov_b64_e32 v[54:55], 0
	v_mov_b64_e32 v[56:57], 0
	v_mov_b64_e32 v[58:59], 0
	v_mov_b64_e32 v[60:61], 0
	v_mov_b64_e32 v[62:63], 0
	v_mov_b64_e32 v[64:65], 0
	v_mov_b64_e32 v[66:67], 0
	v_mov_b64_e32 v[68:69], 0
	v_mov_b64_e32 v[70:71], 0
	v_mov_b64_e32 v[72:73], 0
	v_mov_b64_e32 v[74:75], 0
	v_mov_b64_e32 v[76:77], 0
	v_mov_b64_e32 v[78:79], 0
	v_mov_b64_e32 v[80:81], 0
	v_mov_b64_e32 v[82:83], 0
	v_mov_b64_e32 v[84:85], 0
	v_mov_b64_e32 v[86:87], 0
	v_mov_b64_e32 v[88:89], 0
	v_mov_b64_e32 v[90:91], 0
	v_mov_b64_e32 v[92:93], 0
	v_mov_b64_e32 v[94:95], 0
	v_mov_b64_e32 v[96:97], 0
	v_mov_b64_e32 v[98:99], 0
	v_mov_b64_e32 v[100:101], 0
	v_mov_b64_e32 v[102:103], 0
	v_mov_b64_e32 v[104:105], 0
	v_mov_b64_e32 v[106:107], 0
	v_mov_b64_e32 v[108:109], 0
	v_mov_b64_e32 v[110:111], 0
	v_mov_b64_e32 v[112:113], 0
	v_mov_b64_e32 v[114:115], 0
	v_mov_b64_e32 v[116:117], 0
	v_mov_b64_e32 v[118:119], 0
	v_mov_b64_e32 v[120:121], 0
	v_mov_b64_e32 v[122:123], 0
	v_mov_b64_e32 v[124:125], 0
	v_mov_b64_e32 v[126:127], 0
	s_barrier

.LBB0_683:
	s_ashr_i32 s15, s14, 31
	s_lshl_b64 s[16:17], s[14:15], 20
	s_add_u32 s16, s26, s16
	s_addc_u32 s17, s27, s17
	s_and_b64 s[18:19], s[4:5], exec
	s_cselect_b32 s15, s17, s21
	s_cselect_b32 s42, s16, s20
	s_ashr_i32 s13, s12, 31
	s_lshl_b64 s[18:19], s[12:13], 20
	s_add_u32 s18, s28, s18
	s_addc_u32 s19, s29, s19
	s_and_b64 s[24:25], s[4:5], exec
	s_cselect_b32 s13, s19, s23
	s_cselect_b32 s43, s18, s22
	s_add_u32 s20, s20, 0x80080
	s_addc_u32 s21, s21, 0
	s_add_u32 s44, s22, 0x100
	s_addc_u32 s45, s23, 0
	s_mov_b32 s50, -2
	v_mov_b64_e32 v[0:1], 0
	v_mov_b64_e32 v[2:3], 0
	v_mov_b64_e32 v[4:5], 0
	v_mov_b64_e32 v[6:7], 0
	v_mov_b64_e32 v[8:9], 0
	v_mov_b64_e32 v[10:11], 0
	v_mov_b64_e32 v[12:13], 0
	v_mov_b64_e32 v[14:15], 0
	v_mov_b64_e32 v[16:17], 0
	v_mov_b64_e32 v[18:19], 0
	v_mov_b64_e32 v[20:21], 0
	v_mov_b64_e32 v[22:23], 0
	v_mov_b64_e32 v[24:25], 0
	v_mov_b64_e32 v[26:27], 0
	v_mov_b64_e32 v[28:29], 0
	v_mov_b64_e32 v[30:31], 0
	v_mov_b64_e32 v[32:33], 0
	v_mov_b64_e32 v[34:35], 0
	v_mov_b64_e32 v[36:37], 0
	v_mov_b64_e32 v[38:39], 0
	v_mov_b64_e32 v[40:41], 0
	v_mov_b64_e32 v[42:43], 0
	v_mov_b64_e32 v[44:45], 0
	v_mov_b64_e32 v[46:47], 0
	v_mov_b64_e32 v[48:49], 0
	v_mov_b64_e32 v[50:51], 0
	v_mov_b64_e32 v[52:53], 0
	v_mov_b64_e32 v[54:55], 0
	v_mov_b64_e32 v[56:57], 0
	v_mov_b64_e32 v[58:59], 0
	v_mov_b64_e32 v[60:61], 0
	v_mov_b64_e32 v[62:63], 0
	v_mov_b64_e32 v[64:65], 0
	v_mov_b64_e32 v[66:67], 0
	v_mov_b64_e32 v[68:69], 0
	v_mov_b64_e32 v[70:71], 0
	v_mov_b64_e32 v[72:73], 0
	v_mov_b64_e32 v[74:75], 0
	v_mov_b64_e32 v[76:77], 0
	v_mov_b64_e32 v[78:79], 0
	v_mov_b64_e32 v[80:81], 0
	v_mov_b64_e32 v[82:83], 0
	v_mov_b64_e32 v[84:85], 0
	v_mov_b64_e32 v[86:87], 0
	v_mov_b64_e32 v[88:89], 0
	v_mov_b64_e32 v[90:91], 0
	v_mov_b64_e32 v[92:93], 0
	v_mov_b64_e32 v[94:95], 0
	v_mov_b64_e32 v[96:97], 0
	v_mov_b64_e32 v[98:99], 0
	v_mov_b64_e32 v[100:101], 0
	v_mov_b64_e32 v[102:103], 0
	v_mov_b64_e32 v[104:105], 0
	v_mov_b64_e32 v[106:107], 0
	v_mov_b64_e32 v[108:109], 0
	v_mov_b64_e32 v[110:111], 0
	v_mov_b64_e32 v[112:113], 0
	v_mov_b64_e32 v[114:115], 0
	v_mov_b64_e32 v[116:117], 0
	v_mov_b64_e32 v[118:119], 0
	v_mov_b64_e32 v[120:121], 0
	v_mov_b64_e32 v[122:123], 0
	v_mov_b64_e32 v[124:125], 0
	v_mov_b64_e32 v[126:127], 0
	.p2align 6
